# strategy 7.5 extended: the 128 packed multiplies of the G4 SwiGLU epilogue split into scalar v_mul pairs
# baseline (speedup 1.0000x reference)
; __device__ __forceinline__ unsigned pkbf(float lo, float hi) { f2_t v = {lo, hi}; return __builtin_bit_cast(unsigned, __builtin_convertvector(v, bf2_t)); }
; __device__ __forceinline__ float fsigmoid(float g) { return __builtin_amdgcn_rcpf(1.0f + __builtin_amdgcn_exp2f(-1.44269504f * g)); }
;     __device__ __forceinline__ void operator()(const f32x4 (&acc)[2][2][4][2], const Unit& u, int wr, int wc, int fr, int fq) const {
;     ...
;             for (int m = 0; m < 4; ++m) { const int row = row0 + ai * HALF + m * 16; const float sc = rsqrtf(ss[row] * invk + eps);
;                 float h[8];
; #pragma unroll
;                 for (int n = 0; n < 2; ++n)
; #pragma unroll
;                     for (int j = 0; j < 4; ++j) { const float g = acc[ai][0][m][n][j] * sc, up = acc[ai][1][m][n][j] * sc; h[4 * n + j] = g * fsigmoid(g) * up; }
;                 u32x4 w; w.x = pkbf(h[0], h[1]); w.y = pkbf(h[2], h[3]); w.z = pkbf(h[4], h[5]); w.w = pkbf(h[6], h[7]);
;                 *(u32x4*)(O + (size_t)row * ldc + col0) = w; }
.LBB0_47:
	v_lshl_add_u32 v146, s58, 8, v152
	v_ashrrev_i32_e32 v147, 31, v146
	v_lshl_add_u64 v[148:149], v[146:147], 2, s[8:9]
	global_load_dword v192, v[148:149], off
	global_load_dword v193, v[148:149], off offset:64
	global_load_dword v194, v[148:149], off offset:128
	global_load_dword v195, v[148:149], off offset:192
	global_load_dword v196, v[148:149], off offset:512
	global_load_dword v197, v[148:149], off offset:576
	global_load_dword v198, v[148:149], off offset:640
	global_load_dword v199, v[148:149], off offset:704
	v_lshl_or_b32 v150, s0, 7, v154
	v_ashrrev_i32_e32 v151, 31, v150
	s_mov_b64 s[58:59], -1
	s_waitcnt vmcnt(7)
	v_fmamk_f32 v147, v192, 0x3a800000, v134
	v_cmp_gt_f32_e32 vcc, s13, v147
	v_mul_f32_e32 v156, 0x4b800000, v147
	s_nop 0
	v_cndmask_b32_e32 v147, v147, v156, vcc
	v_rsq_f32_e32 v147, v147
	s_nop 0
	v_mul_f32_e32 v156, 0x45800000, v147
	v_cndmask_b32_e32 v156, v147, v156, vcc
	v_mul_f32_e32 v124, v124, v156
	v_mul_f32_e32 v125, v125, v156
	v_mul_f32_e32 v116, v116, v156
	v_mul_f32_e32 v117, v117, v156
	v_mul_f32_e32 v147, 0xbfb8aa3b, v124
	v_exp_f32_e32 v147, v147
	v_mul_f32_e32 v118, v118, v156
	v_mul_f32_e32 v119, v119, v156
	v_mul_f32_e32 v120, v120, v156
	v_mul_f32_e32 v121, v121, v156
	v_mul_f32_e32 v112, v112, v156
	v_mul_f32_e32 v113, v113, v156
	v_add_f32_e32 v147, 1.0, v147
	v_rcp_f32_e32 v158, v147
	v_mul_f32_e32 v147, 0xbfb8aa3b, v125
	v_exp_f32_e32 v147, v147
	v_mul_f32_e32 v114, v114, v156
	v_mul_f32_e32 v115, v115, v156
	v_add_f32_e32 v147, 1.0, v147
	v_rcp_f32_e32 v159, v147
	s_nop 0
	v_mul_f32_e32 v124, v124, v158
	v_mul_f32_e32 v125, v125, v159
	s_nop 0
	v_mul_f32_e32 v116, v116, v124
	v_mul_f32_e32 v117, v117, v125
	v_mul_f32_e32 v124, v126, v156
	v_mul_f32_e32 v125, v127, v156
	s_nop 0
	v_mul_f32_e32 v126, 0xbfb8aa3b, v124
	v_mul_f32_e32 v127, 0xbfb8aa3b, v125
	v_exp_f32_e32 v126, v126
	v_exp_f32_e32 v127, v127
	v_add_f32_e32 v126, 1.0, v126
	v_add_f32_e32 v127, 1.0, v127
	v_rcp_f32_e32 v126, v126
	v_rcp_f32_e32 v127, v127
	s_nop 0
	v_mul_f32_e32 v124, v124, v126
	v_mul_f32_e32 v125, v125, v127
	s_nop 0
	v_mul_f32_e32 v118, v118, v124
	v_mul_f32_e32 v119, v119, v125
	v_mul_f32_e32 v124, 0xbfb8aa3b, v120
	v_mul_f32_e32 v125, 0xbfb8aa3b, v121
	v_exp_f32_e32 v124, v124
	v_exp_f32_e32 v125, v125
	v_add_f32_e32 v124, 1.0, v124
	v_add_f32_e32 v125, 1.0, v125
	v_rcp_f32_e32 v124, v124
	v_rcp_f32_e32 v125, v125
	s_nop 0
	v_mul_f32_e32 v120, v120, v124
	v_mul_f32_e32 v121, v121, v125
	s_nop 0
	v_mul_f32_e32 v120, v112, v120
	v_mul_f32_e32 v121, v113, v121
	v_mul_f32_e32 v112, v122, v156
	v_mul_f32_e32 v113, v123, v156
	s_nop 0
	v_mul_f32_e32 v122, 0xbfb8aa3b, v112
	v_mul_f32_e32 v123, 0xbfb8aa3b, v113
	v_exp_f32_e32 v122, v122
	v_exp_f32_e32 v123, v123
	v_add_f32_e32 v122, 1.0, v122
	v_add_f32_e32 v123, 1.0, v123
	v_rcp_f32_e32 v122, v122
	v_rcp_f32_e32 v123, v123
	s_nop 0
	v_mul_f32_e32 v112, v112, v122
	v_mul_f32_e32 v113, v113, v123
	s_nop 0
	v_mul_f32_e32 v122, v114, v112
	v_mul_f32_e32 v123, v115, v113
	v_cvt_pk_bf16_f32 v112, v116, v117
	v_mov_b64_e32 v[116:117], s[34:35]
	v_cvt_pk_bf16_f32 v113, v118, v119
	v_cvt_pk_bf16_f32 v114, v120, v121
	v_mad_i64_i32 v[120:121], s[0:1], v146, s73, v[116:117]
	v_lshlrev_b64 v[118:119], 1, v[150:151]
	v_cvt_pk_bf16_f32 v115, v122, v123
	v_lshl_add_u64 v[120:121], v[120:121], 0, v[118:119]
	global_store_dwordx4 v[120:121], v[112:115], off
	s_nop 1
	v_or_b32_e32 v112, 16, v146
	s_waitcnt vmcnt(7)
	v_fmamk_f32 v113, v193, 0x3a800000, v134
	v_cmp_gt_f32_e32 vcc, s13, v113
	v_mul_f32_e32 v114, 0x4b800000, v113
	s_nop 0
	v_cndmask_b32_e32 v113, v113, v114, vcc
	v_rsq_f32_e32 v113, v113
	s_nop 0
	v_mul_f32_e32 v114, 0x45800000, v113
	v_cndmask_b32_e32 v114, v113, v114, vcc
	v_mul_f32_e32 v108, v108, v114
	v_mul_f32_e32 v109, v109, v114
	v_mul_f32_e32 v100, v100, v114
	v_mul_f32_e32 v101, v101, v114
	v_mul_f32_e32 v113, 0xbfb8aa3b, v108
	v_exp_f32_e32 v113, v113
	v_mul_f32_e32 v102, v102, v114
	v_mul_f32_e32 v103, v103, v114
	v_mul_f32_e32 v104, v104, v114
	v_mul_f32_e32 v105, v105, v114
	v_mul_f32_e32 v96, v96, v114
	v_mul_f32_e32 v97, v97, v114
	v_add_f32_e32 v113, 1.0, v113
	v_rcp_f32_e32 v120, v113
	v_mul_f32_e32 v113, 0xbfb8aa3b, v109
	v_exp_f32_e32 v113, v113
	v_mul_f32_e32 v98, v98, v114
	v_mul_f32_e32 v99, v99, v114
	v_add_f32_e32 v113, 1.0, v113
	v_rcp_f32_e32 v121, v113
	s_nop 0
	v_mul_f32_e32 v108, v108, v120
	v_mul_f32_e32 v109, v109, v121
	s_nop 0
	v_mul_f32_e32 v100, v100, v108
	v_mul_f32_e32 v101, v101, v109
	v_mul_f32_e32 v108, v110, v114
	v_mul_f32_e32 v109, v111, v114
	s_nop 0
	v_mul_f32_e32 v110, 0xbfb8aa3b, v108
	v_mul_f32_e32 v111, 0xbfb8aa3b, v109
	v_exp_f32_e32 v110, v110
	v_exp_f32_e32 v111, v111
	v_add_f32_e32 v110, 1.0, v110
	v_add_f32_e32 v111, 1.0, v111
	v_rcp_f32_e32 v110, v110
	v_rcp_f32_e32 v111, v111
	s_nop 0
	v_mul_f32_e32 v108, v108, v110
	v_mul_f32_e32 v109, v109, v111
	s_nop 0
	v_mul_f32_e32 v102, v102, v108
	v_mul_f32_e32 v103, v103, v109
	v_mul_f32_e32 v108, 0xbfb8aa3b, v104
	v_mul_f32_e32 v109, 0xbfb8aa3b, v105
	v_exp_f32_e32 v108, v108
	v_exp_f32_e32 v109, v109
	v_add_f32_e32 v108, 1.0, v108
	v_add_f32_e32 v109, 1.0, v109
	v_rcp_f32_e32 v108, v108
	v_rcp_f32_e32 v109, v109
	s_nop 0
	v_mul_f32_e32 v104, v104, v108
	v_mul_f32_e32 v105, v105, v109
	s_nop 0
	v_mul_f32_e32 v104, v96, v104
	v_mul_f32_e32 v105, v97, v105
	v_mul_f32_e32 v96, v106, v114
	v_mul_f32_e32 v97, v107, v114
	s_nop 0
	v_mul_f32_e32 v106, 0xbfb8aa3b, v96
	v_mul_f32_e32 v107, 0xbfb8aa3b, v97
	v_exp_f32_e32 v106, v106
	v_exp_f32_e32 v107, v107
	v_add_f32_e32 v106, 1.0, v106
	v_add_f32_e32 v107, 1.0, v107
	v_rcp_f32_e32 v106, v106
	v_rcp_f32_e32 v107, v107
	s_nop 0
	v_mul_f32_e32 v96, v96, v106
	v_mul_f32_e32 v97, v97, v107
	s_nop 0
	v_mul_f32_e32 v106, v98, v96
	v_mul_f32_e32 v107, v99, v97
	v_cvt_pk_bf16_f32 v96, v100, v101
	v_mad_i64_i32 v[100:101], s[0:1], v112, s73, v[116:117]
	v_cvt_pk_bf16_f32 v97, v102, v103
	v_cvt_pk_bf16_f32 v98, v104, v105
	v_cvt_pk_bf16_f32 v99, v106, v107
	v_lshl_add_u64 v[100:101], v[100:101], 0, v[118:119]
	global_store_dwordx4 v[100:101], v[96:99], off
	s_nop 1
	v_or_b32_e32 v96, 32, v146
	s_waitcnt vmcnt(7)
; __device__ __forceinline__ unsigned pkbf(float lo, float hi) { f2_t v = {lo, hi}; return __builtin_bit_cast(unsigned, __builtin_convertvector(v, bf2_t)); }
; __device__ __forceinline__ float fsigmoid(float g) { return __builtin_amdgcn_rcpf(1.0f + __builtin_amdgcn_exp2f(-1.44269504f * g)); }
;     __device__ __forceinline__ void operator()(const f32x4 (&acc)[2][2][4][2], const Unit& u, int wr, int wc, int fr, int fq) const {
;     ...
;             for (int m = 0; m < 4; ++m) { const int row = row0 + ai * HALF + m * 16; const float sc = rsqrtf(ss[row] * invk + eps);
;                 float h[8];
; #pragma unroll
;                 for (int n = 0; n < 2; ++n)
; #pragma unroll
;                     for (int j = 0; j < 4; ++j) { const float g = acc[ai][0][m][n][j] * sc, up = acc[ai][1][m][n][j] * sc; h[4 * n + j] = g * fsigmoid(g) * up; }
;                 u32x4 w; w.x = pkbf(h[0], h[1]); w.y = pkbf(h[2], h[3]); w.z = pkbf(h[4], h[5]); w.w = pkbf(h[6], h[7]);
;                 *(u32x4*)(O + (size_t)row * ldc + col0) = w; }
	v_fmamk_f32 v97, v194, 0x3a800000, v134
	v_cmp_gt_f32_e32 vcc, s13, v97
	v_mul_f32_e32 v98, 0x4b800000, v97
	s_nop 0
	v_cndmask_b32_e32 v97, v97, v98, vcc
	v_rsq_f32_e32 v97, v97
	s_nop 0
	v_mul_f32_e32 v98, 0x45800000, v97
	v_cndmask_b32_e32 v98, v97, v98, vcc
	v_mul_f32_e32 v92, v92, v98
	v_mul_f32_e32 v93, v93, v98
	v_mul_f32_e32 v84, v84, v98
	v_mul_f32_e32 v85, v85, v98
	v_mul_f32_e32 v97, 0xbfb8aa3b, v92
	v_exp_f32_e32 v97, v97
	v_mul_f32_e32 v86, v86, v98
	v_mul_f32_e32 v87, v87, v98
	v_mul_f32_e32 v88, v88, v98
	v_mul_f32_e32 v89, v89, v98
	v_mul_f32_e32 v80, v80, v98
	v_mul_f32_e32 v81, v81, v98
	v_add_f32_e32 v97, 1.0, v97
	v_rcp_f32_e32 v100, v97
	v_mul_f32_e32 v97, 0xbfb8aa3b, v93
	v_exp_f32_e32 v97, v97
	v_mul_f32_e32 v82, v82, v98
	v_mul_f32_e32 v83, v83, v98
	v_add_f32_e32 v97, 1.0, v97
	v_rcp_f32_e32 v101, v97
	s_nop 0
	v_mul_f32_e32 v92, v92, v100
	v_mul_f32_e32 v93, v93, v101
	s_nop 0
	v_mul_f32_e32 v84, v84, v92
	v_mul_f32_e32 v85, v85, v93
	v_mul_f32_e32 v92, v94, v98
	v_mul_f32_e32 v93, v95, v98
	s_nop 0
	v_mul_f32_e32 v94, 0xbfb8aa3b, v92
	v_mul_f32_e32 v95, 0xbfb8aa3b, v93
	v_exp_f32_e32 v94, v94
	v_exp_f32_e32 v95, v95
	v_add_f32_e32 v94, 1.0, v94
	v_add_f32_e32 v95, 1.0, v95
	v_rcp_f32_e32 v94, v94
	v_rcp_f32_e32 v95, v95
	s_nop 0
	v_mul_f32_e32 v92, v92, v94
	v_mul_f32_e32 v93, v93, v95
	s_nop 0
	v_mul_f32_e32 v86, v86, v92
	v_mul_f32_e32 v87, v87, v93
	v_mul_f32_e32 v92, 0xbfb8aa3b, v88
	v_mul_f32_e32 v93, 0xbfb8aa3b, v89
	v_exp_f32_e32 v92, v92
	v_exp_f32_e32 v93, v93
	v_add_f32_e32 v92, 1.0, v92
	v_add_f32_e32 v93, 1.0, v93
	v_rcp_f32_e32 v92, v92
	v_rcp_f32_e32 v93, v93
	s_nop 0
	v_mul_f32_e32 v88, v88, v92
	v_mul_f32_e32 v89, v89, v93
	s_nop 0
	v_mul_f32_e32 v88, v80, v88
	v_mul_f32_e32 v89, v81, v89
	v_mul_f32_e32 v80, v90, v98
	v_mul_f32_e32 v81, v91, v98
	s_nop 0
	v_mul_f32_e32 v90, 0xbfb8aa3b, v80
	v_mul_f32_e32 v91, 0xbfb8aa3b, v81
	v_exp_f32_e32 v90, v90
	v_exp_f32_e32 v91, v91
	v_add_f32_e32 v90, 1.0, v90
	v_add_f32_e32 v91, 1.0, v91
	v_rcp_f32_e32 v90, v90
	v_rcp_f32_e32 v91, v91
	s_nop 0
	v_mul_f32_e32 v80, v80, v90
	v_mul_f32_e32 v81, v81, v91
	s_nop 0
	v_mul_f32_e32 v90, v82, v80
	v_mul_f32_e32 v91, v83, v81
	v_cvt_pk_bf16_f32 v80, v84, v85
	v_mad_i64_i32 v[84:85], s[0:1], v96, s73, v[116:117]
	v_cvt_pk_bf16_f32 v81, v86, v87
	v_cvt_pk_bf16_f32 v82, v88, v89
	v_cvt_pk_bf16_f32 v83, v90, v91
	v_lshl_add_u64 v[84:85], v[84:85], 0, v[118:119]
	global_store_dwordx4 v[84:85], v[80:83], off
	s_nop 1
	v_or_b32_e32 v80, 48, v146
	s_waitcnt vmcnt(7)
	v_fmamk_f32 v81, v195, 0x3a800000, v134
	v_cmp_gt_f32_e32 vcc, s13, v81
	v_mul_f32_e32 v82, 0x4b800000, v81
	s_nop 0
	v_cndmask_b32_e32 v81, v81, v82, vcc
	v_rsq_f32_e32 v81, v81
	s_nop 0
	v_mul_f32_e32 v82, 0x45800000, v81
	v_cndmask_b32_e32 v82, v81, v82, vcc
	v_mul_f32_e32 v76, v76, v82
	v_mul_f32_e32 v77, v77, v82
	v_mul_f32_e32 v68, v68, v82
	v_mul_f32_e32 v69, v69, v82
	v_mul_f32_e32 v81, 0xbfb8aa3b, v76
	v_exp_f32_e32 v81, v81
	v_mul_f32_e32 v70, v70, v82
	v_mul_f32_e32 v71, v71, v82
	v_mul_f32_e32 v72, v72, v82
	v_mul_f32_e32 v73, v73, v82
	v_mul_f32_e32 v64, v64, v82
	v_mul_f32_e32 v65, v65, v82
	v_add_f32_e32 v81, 1.0, v81
	v_rcp_f32_e32 v84, v81
	v_mul_f32_e32 v81, 0xbfb8aa3b, v77
	v_exp_f32_e32 v81, v81
	v_mul_f32_e32 v66, v66, v82
	v_mul_f32_e32 v67, v67, v82
	v_add_f32_e32 v81, 1.0, v81
	v_rcp_f32_e32 v85, v81
	s_nop 0
	v_mul_f32_e32 v76, v76, v84
	v_mul_f32_e32 v77, v77, v85
	s_nop 0
	v_mul_f32_e32 v68, v68, v76
	v_mul_f32_e32 v69, v69, v77
	v_mul_f32_e32 v76, v78, v82
	v_mul_f32_e32 v77, v79, v82
	s_nop 0
	v_mul_f32_e32 v78, 0xbfb8aa3b, v76
	v_mul_f32_e32 v79, 0xbfb8aa3b, v77
	v_exp_f32_e32 v78, v78
	v_exp_f32_e32 v79, v79
	v_add_f32_e32 v78, 1.0, v78
	v_add_f32_e32 v79, 1.0, v79
	v_rcp_f32_e32 v78, v78
	v_rcp_f32_e32 v79, v79
	s_nop 0
	v_mul_f32_e32 v76, v76, v78
	v_mul_f32_e32 v77, v77, v79
	s_nop 0
	v_mul_f32_e32 v70, v70, v76
	v_mul_f32_e32 v71, v71, v77
	v_mul_f32_e32 v76, 0xbfb8aa3b, v72
	v_mul_f32_e32 v77, 0xbfb8aa3b, v73
	v_exp_f32_e32 v76, v76
	v_exp_f32_e32 v77, v77
	v_add_f32_e32 v76, 1.0, v76
	v_add_f32_e32 v77, 1.0, v77
	v_rcp_f32_e32 v76, v76
	v_rcp_f32_e32 v77, v77
	s_nop 0
	v_mul_f32_e32 v72, v72, v76
	v_mul_f32_e32 v73, v73, v77
	s_nop 0
	v_mul_f32_e32 v72, v64, v72
	v_mul_f32_e32 v73, v65, v73
	v_mul_f32_e32 v64, v74, v82
	v_mul_f32_e32 v65, v75, v82
	s_nop 0
	v_mul_f32_e32 v74, 0xbfb8aa3b, v64
	v_mul_f32_e32 v75, 0xbfb8aa3b, v65
	v_exp_f32_e32 v74, v74
	v_exp_f32_e32 v75, v75
	v_add_f32_e32 v74, 1.0, v74
	v_add_f32_e32 v75, 1.0, v75
	v_rcp_f32_e32 v74, v74
	v_rcp_f32_e32 v75, v75
	s_nop 0
	v_mul_f32_e32 v64, v64, v74
	v_mul_f32_e32 v65, v65, v75
	s_nop 0
	v_mul_f32_e32 v74, v66, v64
	v_mul_f32_e32 v75, v67, v65
	v_cvt_pk_bf16_f32 v64, v68, v69
	v_mad_i64_i32 v[68:69], s[0:1], v80, s73, v[116:117]
	v_cvt_pk_bf16_f32 v65, v70, v71
	v_cvt_pk_bf16_f32 v66, v72, v73
	v_cvt_pk_bf16_f32 v67, v74, v75
	v_lshl_add_u64 v[68:69], v[68:69], 0, v[118:119]
	global_store_dwordx4 v[68:69], v[64:67], off
	s_nop 1
	v_add_u32_e32 v65, 0x80, v146
	s_waitcnt vmcnt(7)
; __device__ __forceinline__ unsigned pkbf(float lo, float hi) { f2_t v = {lo, hi}; return __builtin_bit_cast(unsigned, __builtin_convertvector(v, bf2_t)); }
; __device__ __forceinline__ float fsigmoid(float g) { return __builtin_amdgcn_rcpf(1.0f + __builtin_amdgcn_exp2f(-1.44269504f * g)); }
;     __device__ __forceinline__ void operator()(const f32x4 (&acc)[2][2][4][2], const Unit& u, int wr, int wc, int fr, int fq) const {
;     ...
;             for (int m = 0; m < 4; ++m) { const int row = row0 + ai * HALF + m * 16; const float sc = rsqrtf(ss[row] * invk + eps);
;                 float h[8];
; #pragma unroll
;                 for (int n = 0; n < 2; ++n)
; #pragma unroll
;                     for (int j = 0; j < 4; ++j) { const float g = acc[ai][0][m][n][j] * sc, up = acc[ai][1][m][n][j] * sc; h[4 * n + j] = g * fsigmoid(g) * up; }
;                 u32x4 w; w.x = pkbf(h[0], h[1]); w.y = pkbf(h[2], h[3]); w.z = pkbf(h[4], h[5]); w.w = pkbf(h[6], h[7]);
;                 *(u32x4*)(O + (size_t)row * ldc + col0) = w; }
	v_fmamk_f32 v64, v196, 0x3a800000, v134
	v_cmp_gt_f32_e32 vcc, s13, v64
	v_mul_f32_e32 v66, 0x4b800000, v64
	s_nop 0
	v_cndmask_b32_e32 v64, v64, v66, vcc
	v_rsq_f32_e32 v64, v64
	s_nop 0
	v_mul_f32_e32 v66, 0x45800000, v64
	v_cndmask_b32_e32 v64, v64, v66, vcc
	v_mul_f32_e32 v60, v60, v64
	v_mul_f32_e32 v61, v61, v64
	v_mul_f32_e32 v52, v52, v64
	v_mul_f32_e32 v53, v53, v64
	v_mul_f32_e32 v66, 0xbfb8aa3b, v60
	v_mul_f32_e32 v67, 0xbfb8aa3b, v61
	v_exp_f32_e32 v66, v66
	v_exp_f32_e32 v67, v67
	v_mul_f32_e32 v54, v54, v64
	v_mul_f32_e32 v55, v55, v64
	v_mul_f32_e32 v56, v56, v64
	v_mul_f32_e32 v57, v57, v64
	v_add_f32_e32 v66, 1.0, v66
	v_add_f32_e32 v67, 1.0, v67
	v_rcp_f32_e32 v66, v66
	v_rcp_f32_e32 v67, v67
	v_mul_f32_e32 v48, v48, v64
	v_mul_f32_e32 v49, v49, v64
	v_mul_f32_e32 v50, v50, v64
	v_mul_f32_e32 v51, v51, v64
	v_mul_f32_e32 v60, v60, v66
	v_mul_f32_e32 v61, v61, v67
	s_nop 0
	v_mul_f32_e32 v52, v52, v60
	v_mul_f32_e32 v53, v53, v61
	v_mul_f32_e32 v60, v62, v64
	v_mul_f32_e32 v61, v63, v64
	s_nop 0
	v_mul_f32_e32 v62, 0xbfb8aa3b, v60
	v_mul_f32_e32 v63, 0xbfb8aa3b, v61
	v_exp_f32_e32 v62, v62
	v_exp_f32_e32 v63, v63
	v_add_f32_e32 v62, 1.0, v62
	v_add_f32_e32 v63, 1.0, v63
	v_rcp_f32_e32 v62, v62
	v_rcp_f32_e32 v63, v63
	s_nop 0
	v_mul_f32_e32 v60, v60, v62
	v_mul_f32_e32 v61, v61, v63
	s_nop 0
	v_mul_f32_e32 v54, v54, v60
	v_mul_f32_e32 v55, v55, v61
	v_mul_f32_e32 v60, 0xbfb8aa3b, v56
	v_mul_f32_e32 v61, 0xbfb8aa3b, v57
	v_exp_f32_e32 v60, v60
	v_exp_f32_e32 v61, v61
	v_add_f32_e32 v60, 1.0, v60
	v_add_f32_e32 v61, 1.0, v61
	v_rcp_f32_e32 v60, v60
	v_rcp_f32_e32 v61, v61
	s_nop 0
	v_mul_f32_e32 v56, v56, v60
	v_mul_f32_e32 v57, v57, v61
	s_nop 0
	v_mul_f32_e32 v56, v48, v56
	v_mul_f32_e32 v57, v49, v57
	v_mul_f32_e32 v48, v58, v64
	v_mul_f32_e32 v49, v59, v64
	s_nop 0
	v_mul_f32_e32 v58, 0xbfb8aa3b, v48
	v_mul_f32_e32 v59, 0xbfb8aa3b, v49
	v_exp_f32_e32 v58, v58
	v_exp_f32_e32 v59, v59
	v_add_f32_e32 v58, 1.0, v58
	v_add_f32_e32 v59, 1.0, v59
	v_rcp_f32_e32 v58, v58
	v_rcp_f32_e32 v59, v59
	s_nop 0
	v_mul_f32_e32 v48, v48, v58
	v_mul_f32_e32 v49, v49, v59
	s_nop 0
	v_mul_f32_e32 v58, v50, v48
	v_mul_f32_e32 v59, v51, v49
	v_cvt_pk_bf16_f32 v48, v52, v53
	v_mad_i64_i32 v[52:53], s[0:1], v65, s73, v[116:117]
	v_cvt_pk_bf16_f32 v49, v54, v55
	v_cvt_pk_bf16_f32 v50, v56, v57
	v_cvt_pk_bf16_f32 v51, v58, v59
	v_lshl_add_u64 v[52:53], v[52:53], 0, v[118:119]
	global_store_dwordx4 v[52:53], v[48:51], off
	s_nop 1
	v_add_u32_e32 v49, 0x90, v146
	s_waitcnt vmcnt(7)
	v_fmamk_f32 v48, v197, 0x3a800000, v134
	v_cmp_gt_f32_e32 vcc, s13, v48
	v_mul_f32_e32 v50, 0x4b800000, v48
	s_nop 0
	v_cndmask_b32_e32 v48, v48, v50, vcc
	v_rsq_f32_e32 v48, v48
	s_nop 0
	v_mul_f32_e32 v50, 0x45800000, v48
	v_cndmask_b32_e32 v48, v48, v50, vcc
	v_mul_f32_e32 v44, v44, v48
	v_mul_f32_e32 v45, v45, v48
	v_mul_f32_e32 v36, v36, v48
	v_mul_f32_e32 v37, v37, v48
	v_mul_f32_e32 v50, 0xbfb8aa3b, v44
	v_mul_f32_e32 v51, 0xbfb8aa3b, v45
	v_exp_f32_e32 v50, v50
	v_exp_f32_e32 v51, v51
	v_mul_f32_e32 v38, v38, v48
	v_mul_f32_e32 v39, v39, v48
	v_mul_f32_e32 v40, v40, v48
	v_mul_f32_e32 v41, v41, v48
	v_add_f32_e32 v50, 1.0, v50
	v_add_f32_e32 v51, 1.0, v51
	v_rcp_f32_e32 v50, v50
	v_rcp_f32_e32 v51, v51
	v_mul_f32_e32 v32, v32, v48
	v_mul_f32_e32 v33, v33, v48
	v_mul_f32_e32 v34, v34, v48
	v_mul_f32_e32 v35, v35, v48
	v_mul_f32_e32 v44, v44, v50
	v_mul_f32_e32 v45, v45, v51
	s_nop 0
	v_mul_f32_e32 v36, v36, v44
	v_mul_f32_e32 v37, v37, v45
	v_mul_f32_e32 v44, v46, v48
	v_mul_f32_e32 v45, v47, v48
	s_nop 0
	v_mul_f32_e32 v46, 0xbfb8aa3b, v44
	v_mul_f32_e32 v47, 0xbfb8aa3b, v45
	v_exp_f32_e32 v46, v46
	v_exp_f32_e32 v47, v47
	v_add_f32_e32 v46, 1.0, v46
	v_add_f32_e32 v47, 1.0, v47
	v_rcp_f32_e32 v46, v46
	v_rcp_f32_e32 v47, v47
	s_nop 0
	v_mul_f32_e32 v44, v44, v46
	v_mul_f32_e32 v45, v45, v47
	s_nop 0
	v_mul_f32_e32 v38, v38, v44
	v_mul_f32_e32 v39, v39, v45
	v_mul_f32_e32 v44, 0xbfb8aa3b, v40
	v_mul_f32_e32 v45, 0xbfb8aa3b, v41
	v_exp_f32_e32 v44, v44
	v_exp_f32_e32 v45, v45
	v_add_f32_e32 v44, 1.0, v44
	v_add_f32_e32 v45, 1.0, v45
	v_rcp_f32_e32 v44, v44
	v_rcp_f32_e32 v45, v45
	s_nop 0
	v_mul_f32_e32 v40, v40, v44
	v_mul_f32_e32 v41, v41, v45
	s_nop 0
	v_mul_f32_e32 v40, v32, v40
	v_mul_f32_e32 v41, v33, v41
	v_mul_f32_e32 v32, v42, v48
	v_mul_f32_e32 v33, v43, v48
	s_nop 0
	v_mul_f32_e32 v42, 0xbfb8aa3b, v32
	v_mul_f32_e32 v43, 0xbfb8aa3b, v33
	v_exp_f32_e32 v42, v42
	v_exp_f32_e32 v43, v43
	v_add_f32_e32 v42, 1.0, v42
	v_add_f32_e32 v43, 1.0, v43
	v_rcp_f32_e32 v42, v42
	v_rcp_f32_e32 v43, v43
	s_nop 0
	v_mul_f32_e32 v32, v32, v42
	v_mul_f32_e32 v33, v33, v43
	s_nop 0
	v_mul_f32_e32 v42, v34, v32
	v_mul_f32_e32 v43, v35, v33
	v_cvt_pk_bf16_f32 v32, v36, v37
	v_mad_i64_i32 v[36:37], s[0:1], v49, s73, v[116:117]
	v_cvt_pk_bf16_f32 v33, v38, v39
	v_cvt_pk_bf16_f32 v34, v40, v41
	v_cvt_pk_bf16_f32 v35, v42, v43
	v_lshl_add_u64 v[36:37], v[36:37], 0, v[118:119]
	global_store_dwordx4 v[36:37], v[32:35], off
	s_nop 1
	v_add_u32_e32 v33, 0xa0, v146
	s_waitcnt vmcnt(7)
; __device__ __forceinline__ unsigned pkbf(float lo, float hi) { f2_t v = {lo, hi}; return __builtin_bit_cast(unsigned, __builtin_convertvector(v, bf2_t)); }
; __device__ __forceinline__ float fsigmoid(float g) { return __builtin_amdgcn_rcpf(1.0f + __builtin_amdgcn_exp2f(-1.44269504f * g)); }
;     __device__ __forceinline__ void operator()(const f32x4 (&acc)[2][2][4][2], const Unit& u, int wr, int wc, int fr, int fq) const {
;     ...
;             for (int m = 0; m < 4; ++m) { const int row = row0 + ai * HALF + m * 16; const float sc = rsqrtf(ss[row] * invk + eps);
;                 float h[8];
; #pragma unroll
;                 for (int n = 0; n < 2; ++n)
; #pragma unroll
;                     for (int j = 0; j < 4; ++j) { const float g = acc[ai][0][m][n][j] * sc, up = acc[ai][1][m][n][j] * sc; h[4 * n + j] = g * fsigmoid(g) * up; }
;                 u32x4 w; w.x = pkbf(h[0], h[1]); w.y = pkbf(h[2], h[3]); w.z = pkbf(h[4], h[5]); w.w = pkbf(h[6], h[7]);
;                 *(u32x4*)(O + (size_t)row * ldc + col0) = w; }
; template <class Epi, class Sched, bool ALIGN_EPI = false, bool SP2 = false>
; __device__ __forceinline__ void gemm_phase(PG8_LAS unsigned char* lds, const Gemm g, const Sched& S, const Epi& E) {
;     ...
;         for (int t = 0; t < nt; t += 2) {
	v_fmamk_f32 v32, v198, 0x3a800000, v134
	v_cmp_gt_f32_e32 vcc, s13, v32
	v_mul_f32_e32 v34, 0x4b800000, v32
	s_nop 0
	v_cndmask_b32_e32 v32, v32, v34, vcc
	v_rsq_f32_e32 v32, v32
	s_nop 0
	v_mul_f32_e32 v34, 0x45800000, v32
	v_cndmask_b32_e32 v32, v32, v34, vcc
	v_mul_f32_e32 v28, v28, v32
	v_mul_f32_e32 v29, v29, v32
	v_mul_f32_e32 v20, v20, v32
	v_mul_f32_e32 v21, v21, v32
	v_mul_f32_e32 v34, 0xbfb8aa3b, v28
	v_mul_f32_e32 v35, 0xbfb8aa3b, v29
	v_exp_f32_e32 v34, v34
	v_exp_f32_e32 v35, v35
	v_mul_f32_e32 v22, v22, v32
	v_mul_f32_e32 v23, v23, v32
	v_mul_f32_e32 v24, v24, v32
	v_mul_f32_e32 v25, v25, v32
	v_add_f32_e32 v34, 1.0, v34
	v_add_f32_e32 v35, 1.0, v35
	v_rcp_f32_e32 v34, v34
	v_rcp_f32_e32 v35, v35
	v_mul_f32_e32 v16, v16, v32
	v_mul_f32_e32 v17, v17, v32
	v_mul_f32_e32 v18, v18, v32
	v_mul_f32_e32 v19, v19, v32
	v_mul_f32_e32 v28, v28, v34
	v_mul_f32_e32 v29, v29, v35
	s_nop 0
	v_mul_f32_e32 v20, v20, v28
	v_mul_f32_e32 v21, v21, v29
	v_mul_f32_e32 v28, v30, v32
	v_mul_f32_e32 v29, v31, v32
	s_nop 0
	v_mul_f32_e32 v30, 0xbfb8aa3b, v28
	v_mul_f32_e32 v31, 0xbfb8aa3b, v29
	v_exp_f32_e32 v30, v30
	v_exp_f32_e32 v31, v31
	v_add_f32_e32 v30, 1.0, v30
	v_add_f32_e32 v31, 1.0, v31
	v_rcp_f32_e32 v30, v30
	v_rcp_f32_e32 v31, v31
	s_nop 0
	v_mul_f32_e32 v28, v28, v30
	v_mul_f32_e32 v29, v29, v31
	s_nop 0
	v_mul_f32_e32 v22, v22, v28
	v_mul_f32_e32 v23, v23, v29
	v_mul_f32_e32 v28, 0xbfb8aa3b, v24
	v_mul_f32_e32 v29, 0xbfb8aa3b, v25
	v_exp_f32_e32 v28, v28
	v_exp_f32_e32 v29, v29
	v_add_f32_e32 v28, 1.0, v28
	v_add_f32_e32 v29, 1.0, v29
	v_rcp_f32_e32 v28, v28
	v_rcp_f32_e32 v29, v29
	s_nop 0
	v_mul_f32_e32 v24, v24, v28
	v_mul_f32_e32 v25, v25, v29
	s_nop 0
	v_mul_f32_e32 v24, v16, v24
	v_mul_f32_e32 v25, v17, v25
	v_mul_f32_e32 v16, v26, v32
	v_mul_f32_e32 v17, v27, v32
	s_nop 0
	v_mul_f32_e32 v26, 0xbfb8aa3b, v16
	v_mul_f32_e32 v27, 0xbfb8aa3b, v17
	v_exp_f32_e32 v26, v26
	v_exp_f32_e32 v27, v27
	v_add_f32_e32 v26, 1.0, v26
	v_add_f32_e32 v27, 1.0, v27
	v_rcp_f32_e32 v26, v26
	v_rcp_f32_e32 v27, v27
	s_nop 0
	v_mul_f32_e32 v16, v16, v26
	v_mul_f32_e32 v17, v17, v27
	s_nop 0
	v_mul_f32_e32 v26, v18, v16
	v_mul_f32_e32 v27, v19, v17
	v_cvt_pk_bf16_f32 v16, v20, v21
	v_mad_i64_i32 v[20:21], s[0:1], v33, s73, v[116:117]
	v_cvt_pk_bf16_f32 v17, v22, v23
	v_cvt_pk_bf16_f32 v18, v24, v25
	v_cvt_pk_bf16_f32 v19, v26, v27
	v_lshl_add_u64 v[20:21], v[20:21], 0, v[118:119]
	global_store_dwordx4 v[20:21], v[16:19], off
	s_nop 1
	v_add_u32_e32 v17, 0xb0, v146
	s_waitcnt vmcnt(7)
	v_fmamk_f32 v16, v199, 0x3a800000, v134
	v_cmp_gt_f32_e32 vcc, s13, v16
	v_mul_f32_e32 v18, 0x4b800000, v16
	s_nop 0
	v_cndmask_b32_e32 v16, v16, v18, vcc
	v_rsq_f32_e32 v16, v16
	s_nop 0
	v_mul_f32_e32 v18, 0x45800000, v16
	v_cndmask_b32_e32 v16, v16, v18, vcc
	v_mul_f32_e32 v12, v12, v16
	v_mul_f32_e32 v13, v13, v16
	v_mul_f32_e32 v4, v4, v16
	v_mul_f32_e32 v5, v5, v16
	v_mul_f32_e32 v18, 0xbfb8aa3b, v12
	v_mul_f32_e32 v19, 0xbfb8aa3b, v13
	v_exp_f32_e32 v18, v18
	v_exp_f32_e32 v19, v19
	v_mul_f32_e32 v6, v6, v16
	v_mul_f32_e32 v7, v7, v16
	v_mul_f32_e32 v8, v8, v16
	v_mul_f32_e32 v9, v9, v16
	v_add_f32_e32 v18, 1.0, v18
	v_add_f32_e32 v19, 1.0, v19
	v_rcp_f32_e32 v18, v18
	v_rcp_f32_e32 v19, v19
	v_mul_f32_e32 v0, v0, v16
	v_mul_f32_e32 v1, v1, v16
	v_mul_f32_e32 v2, v2, v16
	v_mul_f32_e32 v3, v3, v16
	s_andn2_b64 vcc, exec, s[40:41]
	v_mul_f32_e32 v12, v12, v18
	v_mul_f32_e32 v13, v13, v19
	s_nop 0
	v_mul_f32_e32 v4, v4, v12
	v_mul_f32_e32 v5, v5, v13
	v_mul_f32_e32 v12, v14, v16
	v_mul_f32_e32 v13, v15, v16
	s_nop 0
	v_mul_f32_e32 v14, 0xbfb8aa3b, v12
	v_mul_f32_e32 v15, 0xbfb8aa3b, v13
	v_exp_f32_e32 v14, v14
	v_exp_f32_e32 v15, v15
	v_add_f32_e32 v14, 1.0, v14
	v_add_f32_e32 v15, 1.0, v15
	v_rcp_f32_e32 v14, v14
	v_rcp_f32_e32 v15, v15
	s_nop 0
	v_mul_f32_e32 v12, v12, v14
	v_mul_f32_e32 v13, v13, v15
	s_nop 0
	v_mul_f32_e32 v6, v6, v12
	v_mul_f32_e32 v7, v7, v13
	v_mul_f32_e32 v12, 0xbfb8aa3b, v8
	v_mul_f32_e32 v13, 0xbfb8aa3b, v9
	v_exp_f32_e32 v12, v12
	v_exp_f32_e32 v13, v13
	v_add_f32_e32 v12, 1.0, v12
	v_add_f32_e32 v13, 1.0, v13
	v_rcp_f32_e32 v12, v12
	v_rcp_f32_e32 v13, v13
	s_nop 0
	v_mul_f32_e32 v8, v8, v12
	v_mul_f32_e32 v9, v9, v13
	s_nop 0
	v_mul_f32_e32 v8, v0, v8
	v_mul_f32_e32 v9, v1, v9
	v_mul_f32_e32 v0, v10, v16
	v_mul_f32_e32 v1, v11, v16
	s_nop 0
	v_mul_f32_e32 v10, 0xbfb8aa3b, v0
	v_mul_f32_e32 v11, 0xbfb8aa3b, v1
	v_exp_f32_e32 v10, v10
	v_exp_f32_e32 v11, v11
	v_add_f32_e32 v10, 1.0, v10
	v_add_f32_e32 v11, 1.0, v11
	v_rcp_f32_e32 v10, v10
	v_rcp_f32_e32 v11, v11
	s_nop 0
	v_mul_f32_e32 v0, v0, v10
	v_mul_f32_e32 v1, v1, v11
	s_nop 0
	v_mul_f32_e32 v10, v2, v0
	v_mul_f32_e32 v11, v3, v1
	v_cvt_pk_bf16_f32 v0, v4, v5
	v_mad_i64_i32 v[4:5], s[0:1], v17, s73, v[116:117]
	v_cvt_pk_bf16_f32 v1, v6, v7
	v_cvt_pk_bf16_f32 v2, v8, v9
	v_cvt_pk_bf16_f32 v3, v10, v11
	v_lshl_add_u64 v[4:5], v[4:5], 0, v[118:119]
	global_store_dwordx4 v[4:5], v[0:3], off
	s_cbranch_vccnz .LBB0_40
	s_andn2_b64 vcc, exec, s[4:5]
	s_cbranch_vccnz .LBB0_39
	s_barrier
	s_branch .LBB0_39
